# same file, second paired measure
# speedup vs baseline: 1.0103x; 1.0029x over previous
; template <int K> __device__ __forceinline__ float shx(float v) { static_assert(K < 32, "use sum32"); return __int_as_float(__builtin_amdgcn_ds_swizzle(__float_as_int(v), (K << 10) | 0x1f)); }
; #define SBAR() __builtin_amdgcn_sched_barrier(0)
; template <class TIn, class TOut, int ost, bool HAS_SS>
; __device__ __forceinline__ void causal_swa_block(const BlockRef<TIn, TOut>& cur_, const BlockRef<TIn, TOut>& nxt_, int skv, int W, char* lds, Seam<TIn>& S, int cbl  ) {
;     ...
;     for (int r = 0; r < 16; ++r) { const unsigned rowoff = ob0 + (unsigned)(((r & 3) + 8 * (r >> 2)) * ost * 2); float ss_ = 0.f;
; #pragma unroll
;         for (int d0 = 0; d0 < 4; ++d0) { const float v = o[d0][r] * rli[r]; ss_ += v * v;
;             const float vn = shx<1>(v);
;             if ((r32e & 1) == 0) *(unsigned*)(Ob + rowoff + d0 * 64) = cvtpk(v, vn); }
;         if (HAS_SS) { ss_ += shx<1>(ss_); ss_ += shx<2>(ss_); ss_ += shx<4>(ss_); ss_ += shx<8>(ss_); ss_ += shx<16>(ss_);
;             if (r32e == 0) *(float*)((char*)cur.SS + (unsigned)(wid * QBLK + 4 * hie + (r & 3) + 8 * (r >> 2)) * 32u) = ss_; }
;         SBAR(); }
.LBB0_932:
	s_or_b64 exec, exec, s[12:13]
	v_mul_f32_e32 v14, v48, v48
	v_fmac_f32_e32 v14, v0, v0
	v_fmac_f32_e32 v14, v32, v32
	v_fmac_f32_e32 v14, v16, v16
	s_nop 1
	v_mov_b32_dpp v0, v14 quad_perm:[1,0,3,2] row_mask:0xf bank_mask:0xf
	v_cmp_eq_u32_e64 s[34:35], 0, v198
	s_waitcnt lgkmcnt(0)
	v_add_f32_e32 v0, v14, v0
	s_nop 1
	v_mov_b32_dpp v14, v0 quad_perm:[2,3,0,1] row_mask:0xf bank_mask:0xf
	s_waitcnt lgkmcnt(0)
	v_add_f32_e32 v0, v0, v14
	s_nop 1
	v_mov_b32_dpp v14, v0 quad_perm:[3,2,1,0] row_mask:0xf bank_mask:0xf
	s_nop 1
	v_mov_b32_dpp v14, v14 row_half_mirror row_mask:0xf bank_mask:0xf
	s_waitcnt lgkmcnt(0)
	v_add_f32_e32 v0, v0, v14
	s_nop 1
	v_mov_b32_dpp v14, v0 row_half_mirror row_mask:0xf bank_mask:0xf
	s_nop 1
	v_mov_b32_dpp v14, v14 row_mirror row_mask:0xf bank_mask:0xf
	s_waitcnt lgkmcnt(0)
	v_add_f32_e32 v0, v0, v14
	v_mov_b32_e32 v14, v0
	v_mov_b32_e32 v253, v0
	s_nop 1
	v_permlane16_swap_b32_e32 v14, v253
	s_mov_b32 s98, 0xffff
	s_mov_b32 s99, 0xffff
	v_cndmask_b32_e64 v14, v14, v253, s[98:99]
	s_and_saveexec_b64 s[12:13], s[34:35]
	s_cbranch_execz .LBB0_934
	s_waitcnt lgkmcnt(0)
	v_add_f32_e32 v16, v0, v14
	v_lshlrev_b32_e32 v0, 5, v80
	v_lshl_add_u64 v[14:15], s[86:87], 0, v[0:1]
	global_store_dword v[14:15], v16, off

; template <int K> __device__ __forceinline__ float shx(float v) { static_assert(K < 32, "use sum32"); return __int_as_float(__builtin_amdgcn_ds_swizzle(__float_as_int(v), (K << 10) | 0x1f)); }
; #define SBAR() __builtin_amdgcn_sched_barrier(0)
; template <class TIn, class TOut, int ost, bool HAS_SS>
; __device__ __forceinline__ void causal_swa_block(const BlockRef<TIn, TOut>& cur_, const BlockRef<TIn, TOut>& nxt_, int skv, int W, char* lds, Seam<TIn>& S, int cbl  ) {
;     ...
;     for (int r = 0; r < 16; ++r) { const unsigned rowoff = ob0 + (unsigned)(((r & 3) + 8 * (r >> 2)) * ost * 2); float ss_ = 0.f;
; #pragma unroll
;         for (int d0 = 0; d0 < 4; ++d0) { const float v = o[d0][r] * rli[r]; ss_ += v * v;
;             const float vn = shx<1>(v);
;             if ((r32e & 1) == 0) *(unsigned*)(Ob + rowoff + d0 * 64) = cvtpk(v, vn); }
;         if (HAS_SS) { ss_ += shx<1>(ss_); ss_ += shx<2>(ss_); ss_ += shx<4>(ss_); ss_ += shx<8>(ss_); ss_ += shx<16>(ss_);
;             if (r32e == 0) *(float*)((char*)cur.SS + (unsigned)(wid * QBLK + 4 * hie + (r & 3) + 8 * (r >> 2)) * 32u) = ss_; }
;         SBAR(); }
.LBB0_942:
	s_or_b64 exec, exec, s[12:13]
	v_mul_f32_e32 v14, v48, v48
	v_fmac_f32_e32 v14, v0, v0
	v_fmac_f32_e32 v14, v33, v33
	v_fmac_f32_e32 v14, v17, v17
	s_nop 1
	v_mov_b32_dpp v0, v14 quad_perm:[1,0,3,2] row_mask:0xf bank_mask:0xf
	s_waitcnt lgkmcnt(0)
	v_add_f32_e32 v0, v14, v0
	s_nop 1
	v_mov_b32_dpp v14, v0 quad_perm:[2,3,0,1] row_mask:0xf bank_mask:0xf
	s_waitcnt lgkmcnt(0)
	v_add_f32_e32 v0, v0, v14
	s_nop 1
	v_mov_b32_dpp v14, v0 quad_perm:[3,2,1,0] row_mask:0xf bank_mask:0xf
	s_nop 1
	v_mov_b32_dpp v14, v14 row_half_mirror row_mask:0xf bank_mask:0xf
	s_waitcnt lgkmcnt(0)
	v_add_f32_e32 v0, v0, v14
	s_nop 1
	v_mov_b32_dpp v14, v0 row_half_mirror row_mask:0xf bank_mask:0xf
	s_nop 1
	v_mov_b32_dpp v14, v14 row_mirror row_mask:0xf bank_mask:0xf
	s_waitcnt lgkmcnt(0)
	v_add_f32_e32 v0, v0, v14
	v_mov_b32_e32 v14, v0
	v_mov_b32_e32 v253, v0
	s_nop 1
	v_permlane16_swap_b32_e32 v14, v253
	s_mov_b32 s98, 0xffff
	s_mov_b32 s99, 0xffff
	v_cndmask_b32_e64 v14, v14, v253, s[98:99]
	s_and_saveexec_b64 s[12:13], s[34:35]
	s_cbranch_execz .LBB0_944
	s_waitcnt lgkmcnt(0)
	v_add_f32_e32 v17, v0, v14
	v_lshlrev_b32_e32 v0, 5, v16
	v_lshl_add_u64 v[14:15], s[86:87], 0, v[0:1]
	global_store_dword v[14:15], v17, off

; template <int K> __device__ __forceinline__ float shx(float v) { static_assert(K < 32, "use sum32"); return __int_as_float(__builtin_amdgcn_ds_swizzle(__float_as_int(v), (K << 10) | 0x1f)); }
; #define SBAR() __builtin_amdgcn_sched_barrier(0)
; template <class TIn, class TOut, int ost, bool HAS_SS>
; __device__ __forceinline__ void causal_swa_block(const BlockRef<TIn, TOut>& cur_, const BlockRef<TIn, TOut>& nxt_, int skv, int W, char* lds, Seam<TIn>& S, int cbl  ) {
;     ...
;     for (int r = 0; r < 16; ++r) { const unsigned rowoff = ob0 + (unsigned)(((r & 3) + 8 * (r >> 2)) * ost * 2); float ss_ = 0.f;
; #pragma unroll
;         for (int d0 = 0; d0 < 4; ++d0) { const float v = o[d0][r] * rli[r]; ss_ += v * v;
;             const float vn = shx<1>(v);
;             if ((r32e & 1) == 0) *(unsigned*)(Ob + rowoff + d0 * 64) = cvtpk(v, vn); }
;         if (HAS_SS) { ss_ += shx<1>(ss_); ss_ += shx<2>(ss_); ss_ += shx<4>(ss_); ss_ += shx<8>(ss_); ss_ += shx<16>(ss_);
;             if (r32e == 0) *(float*)((char*)cur.SS + (unsigned)(wid * QBLK + 4 * hie + (r & 3) + 8 * (r >> 2)) * 32u) = ss_; }
;         SBAR(); }
.LBB0_952:
	s_or_b64 exec, exec, s[12:13]
	v_mul_f32_e32 v14, v32, v32
	v_fmac_f32_e32 v14, v0, v0
	v_fmac_f32_e32 v14, v33, v33
	v_fmac_f32_e32 v14, v17, v17
	s_nop 1
	v_mov_b32_dpp v0, v14 quad_perm:[1,0,3,2] row_mask:0xf bank_mask:0xf
	s_waitcnt lgkmcnt(0)
	v_add_f32_e32 v0, v14, v0
	s_nop 1
	v_mov_b32_dpp v14, v0 quad_perm:[2,3,0,1] row_mask:0xf bank_mask:0xf
	s_waitcnt lgkmcnt(0)
	v_add_f32_e32 v0, v0, v14
	s_nop 1
	v_mov_b32_dpp v14, v0 quad_perm:[3,2,1,0] row_mask:0xf bank_mask:0xf
	s_nop 1
	v_mov_b32_dpp v14, v14 row_half_mirror row_mask:0xf bank_mask:0xf
	s_waitcnt lgkmcnt(0)
	v_add_f32_e32 v0, v0, v14
	s_nop 1
	v_mov_b32_dpp v14, v0 row_half_mirror row_mask:0xf bank_mask:0xf
	s_nop 1
	v_mov_b32_dpp v14, v14 row_mirror row_mask:0xf bank_mask:0xf
	s_waitcnt lgkmcnt(0)
	v_add_f32_e32 v0, v0, v14
	v_mov_b32_e32 v14, v0
	v_mov_b32_e32 v253, v0
	s_nop 1
	v_permlane16_swap_b32_e32 v14, v253
	s_mov_b32 s98, 0xffff
	s_mov_b32 s99, 0xffff
	v_cndmask_b32_e64 v14, v14, v253, s[98:99]
	s_and_saveexec_b64 s[12:13], s[34:35]
	s_cbranch_execz .LBB0_954
	s_waitcnt lgkmcnt(0)
	v_add_f32_e32 v17, v0, v14
	v_lshlrev_b32_e32 v0, 5, v16
	v_lshl_add_u64 v[14:15], s[86:87], 0, v[0:1]
	global_store_dword v[14:15], v17, off

; template <int K> __device__ __forceinline__ float shx(float v) { static_assert(K < 32, "use sum32"); return __int_as_float(__builtin_amdgcn_ds_swizzle(__float_as_int(v), (K << 10) | 0x1f)); }
; #define SBAR() __builtin_amdgcn_sched_barrier(0)
; template <class TIn, class TOut, int ost, bool HAS_SS>
; __device__ __forceinline__ void causal_swa_block(const BlockRef<TIn, TOut>& cur_, const BlockRef<TIn, TOut>& nxt_, int skv, int W, char* lds, Seam<TIn>& S, int cbl  ) {
;     ...
;     for (int r = 0; r < 16; ++r) { const unsigned rowoff = ob0 + (unsigned)(((r & 3) + 8 * (r >> 2)) * ost * 2); float ss_ = 0.f;
; #pragma unroll
;         for (int d0 = 0; d0 < 4; ++d0) { const float v = o[d0][r] * rli[r]; ss_ += v * v;
;             const float vn = shx<1>(v);
;             if ((r32e & 1) == 0) *(unsigned*)(Ob + rowoff + d0 * 64) = cvtpk(v, vn); }
;         if (HAS_SS) { ss_ += shx<1>(ss_); ss_ += shx<2>(ss_); ss_ += shx<4>(ss_); ss_ += shx<8>(ss_); ss_ += shx<16>(ss_);
;             if (r32e == 0) *(float*)((char*)cur.SS + (unsigned)(wid * QBLK + 4 * hie + (r & 3) + 8 * (r >> 2)) * 32u) = ss_; }
;         SBAR(); }
.LBB0_962:
	s_or_b64 exec, exec, s[12:13]
	v_mul_f32_e32 v14, v18, v18
	v_fmac_f32_e32 v14, v0, v0
	v_fmac_f32_e32 v14, v32, v32
	v_fmac_f32_e32 v14, v17, v17
	s_nop 1
	v_mov_b32_dpp v0, v14 quad_perm:[1,0,3,2] row_mask:0xf bank_mask:0xf
	s_waitcnt lgkmcnt(0)
	v_add_f32_e32 v0, v14, v0
	s_nop 1
	v_mov_b32_dpp v14, v0 quad_perm:[2,3,0,1] row_mask:0xf bank_mask:0xf
	s_waitcnt lgkmcnt(0)
	v_add_f32_e32 v0, v0, v14
	s_nop 1
	v_mov_b32_dpp v14, v0 quad_perm:[3,2,1,0] row_mask:0xf bank_mask:0xf
	s_nop 1
	v_mov_b32_dpp v14, v14 row_half_mirror row_mask:0xf bank_mask:0xf
	s_waitcnt lgkmcnt(0)
	v_add_f32_e32 v0, v0, v14
	s_nop 1
	v_mov_b32_dpp v14, v0 row_half_mirror row_mask:0xf bank_mask:0xf
	s_nop 1
	v_mov_b32_dpp v14, v14 row_mirror row_mask:0xf bank_mask:0xf
	s_waitcnt lgkmcnt(0)
	v_add_f32_e32 v0, v0, v14
	v_mov_b32_e32 v14, v0
	v_mov_b32_e32 v253, v0
	s_nop 1
	v_permlane16_swap_b32_e32 v14, v253
	s_mov_b32 s98, 0xffff
	s_mov_b32 s99, 0xffff
	v_cndmask_b32_e64 v14, v14, v253, s[98:99]
	s_and_saveexec_b64 s[12:13], s[34:35]
	s_cbranch_execz .LBB0_964
	s_waitcnt lgkmcnt(0)
	v_add_f32_e32 v17, v0, v14
	v_lshlrev_b32_e32 v0, 5, v16
	v_lshl_add_u64 v[14:15], s[86:87], 0, v[0:1]
	global_store_dword v[14:15], v17, off

; template <int K> __device__ __forceinline__ float shx(float v) { static_assert(K < 32, "use sum32"); return __int_as_float(__builtin_amdgcn_ds_swizzle(__float_as_int(v), (K << 10) | 0x1f)); }
; #define SBAR() __builtin_amdgcn_sched_barrier(0)
; template <class TIn, class TOut, int ost, bool HAS_SS>
; __device__ __forceinline__ void causal_swa_block(const BlockRef<TIn, TOut>& cur_, const BlockRef<TIn, TOut>& nxt_, int skv, int W, char* lds, Seam<TIn>& S, int cbl  ) {
;     ...
;     for (int r = 0; r < 16; ++r) { const unsigned rowoff = ob0 + (unsigned)(((r & 3) + 8 * (r >> 2)) * ost * 2); float ss_ = 0.f;
; #pragma unroll
;         for (int d0 = 0; d0 < 4; ++d0) { const float v = o[d0][r] * rli[r]; ss_ += v * v;
;             const float vn = shx<1>(v);
;             if ((r32e & 1) == 0) *(unsigned*)(Ob + rowoff + d0 * 64) = cvtpk(v, vn); }
;         if (HAS_SS) { ss_ += shx<1>(ss_); ss_ += shx<2>(ss_); ss_ += shx<4>(ss_); ss_ += shx<8>(ss_); ss_ += shx<16>(ss_);
;             if (r32e == 0) *(float*)((char*)cur.SS + (unsigned)(wid * QBLK + 4 * hie + (r & 3) + 8 * (r >> 2)) * 32u) = ss_; }
;         SBAR(); }
.LBB0_972:
	s_or_b64 exec, exec, s[12:13]
	v_mul_f32_e32 v14, v17, v17
	v_fmac_f32_e32 v14, v0, v0
	v_fmac_f32_e32 v14, v18, v18
	v_fmac_f32_e32 v14, v16, v16
	s_nop 1
	v_mov_b32_dpp v0, v14 quad_perm:[1,0,3,2] row_mask:0xf bank_mask:0xf
	s_waitcnt lgkmcnt(0)
	v_add_f32_e32 v0, v14, v0
	s_nop 1
	v_mov_b32_dpp v14, v0 quad_perm:[2,3,0,1] row_mask:0xf bank_mask:0xf
	s_waitcnt lgkmcnt(0)
	v_add_f32_e32 v0, v0, v14
	s_nop 1
	v_mov_b32_dpp v14, v0 quad_perm:[3,2,1,0] row_mask:0xf bank_mask:0xf
	s_nop 1
	v_mov_b32_dpp v14, v14 row_half_mirror row_mask:0xf bank_mask:0xf
	s_waitcnt lgkmcnt(0)
	v_add_f32_e32 v0, v0, v14
	s_nop 1
	v_mov_b32_dpp v14, v0 row_half_mirror row_mask:0xf bank_mask:0xf
	s_nop 1
	v_mov_b32_dpp v14, v14 row_mirror row_mask:0xf bank_mask:0xf
	s_waitcnt lgkmcnt(0)
	v_add_f32_e32 v0, v0, v14
	v_mov_b32_e32 v14, v0
	v_mov_b32_e32 v253, v0
	s_nop 1
	v_permlane16_swap_b32_e32 v14, v253
	s_mov_b32 s98, 0xffff
	s_mov_b32 s99, 0xffff
	v_cndmask_b32_e64 v14, v14, v253, s[98:99]
	s_and_saveexec_b64 s[12:13], s[34:35]
	s_cbranch_execz .LBB0_974
	s_waitcnt lgkmcnt(0)
	v_add_f32_e32 v16, v0, v14
	v_lshlrev_b32_e32 v0, 5, v10
	v_lshl_add_u64 v[14:15], s[86:87], 0, v[0:1]
	global_store_dword v[14:15], v16, off

; template <int K> __device__ __forceinline__ float shx(float v) { static_assert(K < 32, "use sum32"); return __int_as_float(__builtin_amdgcn_ds_swizzle(__float_as_int(v), (K << 10) | 0x1f)); }
; #define SBAR() __builtin_amdgcn_sched_barrier(0)
; template <class TIn, class TOut, int ost, bool HAS_SS>
; __device__ __forceinline__ void causal_swa_block(const BlockRef<TIn, TOut>& cur_, const BlockRef<TIn, TOut>& nxt_, int skv, int W, char* lds, Seam<TIn>& S, int cbl  ) {
;     ...
;     for (int r = 0; r < 16; ++r) { const unsigned rowoff = ob0 + (unsigned)(((r & 3) + 8 * (r >> 2)) * ost * 2); float ss_ = 0.f;
; #pragma unroll
;         for (int d0 = 0; d0 < 4; ++d0) { const float v = o[d0][r] * rli[r]; ss_ += v * v;
;             const float vn = shx<1>(v);
;             if ((r32e & 1) == 0) *(unsigned*)(Ob + rowoff + d0 * 64) = cvtpk(v, vn); }
;         if (HAS_SS) { ss_ += shx<1>(ss_); ss_ += shx<2>(ss_); ss_ += shx<4>(ss_); ss_ += shx<8>(ss_); ss_ += shx<16>(ss_);
;             if (r32e == 0) *(float*)((char*)cur.SS + (unsigned)(wid * QBLK + 4 * hie + (r & 3) + 8 * (r >> 2)) * 32u) = ss_; }
;         SBAR(); }
.LBB0_982:
	s_or_b64 exec, exec, s[12:13]
	v_mul_f32_e32 v10, v16, v16
	v_fmac_f32_e32 v10, v0, v0
	v_fmac_f32_e32 v10, v17, v17
	v_fmac_f32_e32 v10, v15, v15
	s_nop 1
	v_mov_b32_dpp v0, v10 quad_perm:[1,0,3,2] row_mask:0xf bank_mask:0xf
	s_waitcnt lgkmcnt(0)
	v_add_f32_e32 v0, v10, v0
	s_nop 1
	v_mov_b32_dpp v10, v0 quad_perm:[2,3,0,1] row_mask:0xf bank_mask:0xf
	s_waitcnt lgkmcnt(0)
	v_add_f32_e32 v0, v0, v10
	s_nop 1
	v_mov_b32_dpp v10, v0 quad_perm:[3,2,1,0] row_mask:0xf bank_mask:0xf
	s_nop 1
	v_mov_b32_dpp v10, v10 row_half_mirror row_mask:0xf bank_mask:0xf
	s_waitcnt lgkmcnt(0)
	v_add_f32_e32 v0, v0, v10
	s_nop 1
	v_mov_b32_dpp v10, v0 row_half_mirror row_mask:0xf bank_mask:0xf
	s_nop 1
	v_mov_b32_dpp v10, v10 row_mirror row_mask:0xf bank_mask:0xf
	s_waitcnt lgkmcnt(0)
	v_add_f32_e32 v0, v0, v10
	v_mov_b32_e32 v10, v0
	v_mov_b32_e32 v253, v0
	s_nop 1
	v_permlane16_swap_b32_e32 v10, v253
	s_mov_b32 s98, 0xffff
	s_mov_b32 s99, 0xffff
	v_cndmask_b32_e64 v10, v10, v253, s[98:99]
	s_and_saveexec_b64 s[12:13], s[34:35]
	s_cbranch_execz .LBB0_984
	s_waitcnt lgkmcnt(0)
	v_add_f32_e32 v15, v0, v10
	v_lshlrev_b32_e32 v0, 5, v14
	v_lshl_add_u64 v[10:11], s[86:87], 0, v[0:1]
	global_store_dword v[10:11], v15, off

; template <int K> __device__ __forceinline__ float shx(float v) { static_assert(K < 32, "use sum32"); return __int_as_float(__builtin_amdgcn_ds_swizzle(__float_as_int(v), (K << 10) | 0x1f)); }
; #define SBAR() __builtin_amdgcn_sched_barrier(0)
; template <class TIn, class TOut, int ost, bool HAS_SS>
; __device__ __forceinline__ void causal_swa_block(const BlockRef<TIn, TOut>& cur_, const BlockRef<TIn, TOut>& nxt_, int skv, int W, char* lds, Seam<TIn>& S, int cbl  ) {
;     ...
;     for (int r = 0; r < 16; ++r) { const unsigned rowoff = ob0 + (unsigned)(((r & 3) + 8 * (r >> 2)) * ost * 2); float ss_ = 0.f;
; #pragma unroll
;         for (int d0 = 0; d0 < 4; ++d0) { const float v = o[d0][r] * rli[r]; ss_ += v * v;
;             const float vn = shx<1>(v);
;             if ((r32e & 1) == 0) *(unsigned*)(Ob + rowoff + d0 * 64) = cvtpk(v, vn); }
;         if (HAS_SS) { ss_ += shx<1>(ss_); ss_ += shx<2>(ss_); ss_ += shx<4>(ss_); ss_ += shx<8>(ss_); ss_ += shx<16>(ss_);
;             if (r32e == 0) *(float*)((char*)cur.SS + (unsigned)(wid * QBLK + 4 * hie + (r & 3) + 8 * (r >> 2)) * 32u) = ss_; }
;         SBAR(); }
.LBB0_992:
	s_or_b64 exec, exec, s[12:13]
	v_mul_f32_e32 v10, v15, v15
	v_fmac_f32_e32 v10, v0, v0
	v_fmac_f32_e32 v10, v16, v16
	v_fmac_f32_e32 v10, v14, v14
	s_nop 1
	v_mov_b32_dpp v0, v10 quad_perm:[1,0,3,2] row_mask:0xf bank_mask:0xf
	s_waitcnt lgkmcnt(0)
	v_add_f32_e32 v0, v10, v0
	s_nop 1
	v_mov_b32_dpp v10, v0 quad_perm:[2,3,0,1] row_mask:0xf bank_mask:0xf
	s_waitcnt lgkmcnt(0)
	v_add_f32_e32 v0, v0, v10
	s_nop 1
	v_mov_b32_dpp v10, v0 quad_perm:[3,2,1,0] row_mask:0xf bank_mask:0xf
	s_nop 1
	v_mov_b32_dpp v10, v10 row_half_mirror row_mask:0xf bank_mask:0xf
	s_waitcnt lgkmcnt(0)
	v_add_f32_e32 v0, v0, v10
	s_nop 1
	v_mov_b32_dpp v10, v0 row_half_mirror row_mask:0xf bank_mask:0xf
	s_nop 1
	v_mov_b32_dpp v10, v10 row_mirror row_mask:0xf bank_mask:0xf
	s_waitcnt lgkmcnt(0)
	v_add_f32_e32 v0, v0, v10
	v_mov_b32_e32 v10, v0
	v_mov_b32_e32 v253, v0
	s_nop 1
	v_permlane16_swap_b32_e32 v10, v253
	s_mov_b32 s98, 0xffff
	s_mov_b32 s99, 0xffff
	v_cndmask_b32_e64 v10, v10, v253, s[98:99]
	s_and_saveexec_b64 s[12:13], s[34:35]
	s_cbranch_execz .LBB0_994
	s_waitcnt lgkmcnt(0)
	v_add_f32_e32 v14, v0, v10
	v_lshlrev_b32_e32 v0, 5, v12
	v_lshl_add_u64 v[10:11], s[86:87], 0, v[0:1]
	global_store_dword v[10:11], v14, off

; template <int K> __device__ __forceinline__ float shx(float v) { static_assert(K < 32, "use sum32"); return __int_as_float(__builtin_amdgcn_ds_swizzle(__float_as_int(v), (K << 10) | 0x1f)); }
; #define SBAR() __builtin_amdgcn_sched_barrier(0)
; template <class TIn, class TOut, int ost, bool HAS_SS>
; __device__ __forceinline__ void causal_swa_block(const BlockRef<TIn, TOut>& cur_, const BlockRef<TIn, TOut>& nxt_, int skv, int W, char* lds, Seam<TIn>& S, int cbl  ) {
;     ...
;     for (int r = 0; r < 16; ++r) { const unsigned rowoff = ob0 + (unsigned)(((r & 3) + 8 * (r >> 2)) * ost * 2); float ss_ = 0.f;
; #pragma unroll
;         for (int d0 = 0; d0 < 4; ++d0) { const float v = o[d0][r] * rli[r]; ss_ += v * v;
;             const float vn = shx<1>(v);
;             if ((r32e & 1) == 0) *(unsigned*)(Ob + rowoff + d0 * 64) = cvtpk(v, vn); }
;         if (HAS_SS) { ss_ += shx<1>(ss_); ss_ += shx<2>(ss_); ss_ += shx<4>(ss_); ss_ += shx<8>(ss_); ss_ += shx<16>(ss_);
;             if (r32e == 0) *(float*)((char*)cur.SS + (unsigned)(wid * QBLK + 4 * hie + (r & 3) + 8 * (r >> 2)) * 32u) = ss_; }
;         SBAR(); }
.LBB0_1002:
	s_or_b64 exec, exec, s[12:13]
	v_mul_f32_e32 v10, v14, v14
	v_fmac_f32_e32 v10, v0, v0
	v_fmac_f32_e32 v10, v15, v15
	v_fmac_f32_e32 v10, v13, v13
	s_nop 1
	v_mov_b32_dpp v0, v10 quad_perm:[1,0,3,2] row_mask:0xf bank_mask:0xf
	s_waitcnt lgkmcnt(0)
	v_add_f32_e32 v0, v10, v0
	s_nop 1
	v_mov_b32_dpp v10, v0 quad_perm:[2,3,0,1] row_mask:0xf bank_mask:0xf
	s_waitcnt lgkmcnt(0)
	v_add_f32_e32 v0, v0, v10
	s_nop 1
	v_mov_b32_dpp v10, v0 quad_perm:[3,2,1,0] row_mask:0xf bank_mask:0xf
	s_nop 1
	v_mov_b32_dpp v10, v10 row_half_mirror row_mask:0xf bank_mask:0xf
	s_waitcnt lgkmcnt(0)
	v_add_f32_e32 v0, v0, v10
	s_nop 1
	v_mov_b32_dpp v10, v0 row_half_mirror row_mask:0xf bank_mask:0xf
	s_nop 1
	v_mov_b32_dpp v10, v10 row_mirror row_mask:0xf bank_mask:0xf
	s_waitcnt lgkmcnt(0)
	v_add_f32_e32 v0, v0, v10
	v_mov_b32_e32 v10, v0
	v_mov_b32_e32 v253, v0
	s_nop 1
	v_permlane16_swap_b32_e32 v10, v253
	s_mov_b32 s98, 0xffff
	s_mov_b32 s99, 0xffff
	v_cndmask_b32_e64 v10, v10, v253, s[98:99]
	s_and_saveexec_b64 s[12:13], s[34:35]
	s_cbranch_execz .LBB0_1004
	s_waitcnt lgkmcnt(0)
	v_add_f32_e32 v13, v0, v10
	v_lshlrev_b32_e32 v0, 5, v12
	v_lshl_add_u64 v[10:11], s[86:87], 0, v[0:1]
	global_store_dword v[10:11], v13, off

; template <int K> __device__ __forceinline__ float shx(float v) { static_assert(K < 32, "use sum32"); return __int_as_float(__builtin_amdgcn_ds_swizzle(__float_as_int(v), (K << 10) | 0x1f)); }
; #define SBAR() __builtin_amdgcn_sched_barrier(0)
; template <class TIn, class TOut, int ost, bool HAS_SS>
; __device__ __forceinline__ void causal_swa_block(const BlockRef<TIn, TOut>& cur_, const BlockRef<TIn, TOut>& nxt_, int skv, int W, char* lds, Seam<TIn>& S, int cbl  ) {
;     ...
;     for (int r = 0; r < 16; ++r) { const unsigned rowoff = ob0 + (unsigned)(((r & 3) + 8 * (r >> 2)) * ost * 2); float ss_ = 0.f;
; #pragma unroll
;         for (int d0 = 0; d0 < 4; ++d0) { const float v = o[d0][r] * rli[r]; ss_ += v * v;
;             const float vn = shx<1>(v);
;             if ((r32e & 1) == 0) *(unsigned*)(Ob + rowoff + d0 * 64) = cvtpk(v, vn); }
;         if (HAS_SS) { ss_ += shx<1>(ss_); ss_ += shx<2>(ss_); ss_ += shx<4>(ss_); ss_ += shx<8>(ss_); ss_ += shx<16>(ss_);
;             if (r32e == 0) *(float*)((char*)cur.SS + (unsigned)(wid * QBLK + 4 * hie + (r & 3) + 8 * (r >> 2)) * 32u) = ss_; }
;         SBAR(); }
.LBB0_1012:
	s_or_b64 exec, exec, s[12:13]
	v_mul_f32_e32 v10, v13, v13
	v_fmac_f32_e32 v10, v0, v0
	v_fmac_f32_e32 v10, v14, v14
	v_fmac_f32_e32 v10, v12, v12
	s_nop 1
	v_mov_b32_dpp v0, v10 quad_perm:[1,0,3,2] row_mask:0xf bank_mask:0xf
	s_waitcnt lgkmcnt(0)
	v_add_f32_e32 v0, v10, v0
	s_nop 1
	v_mov_b32_dpp v10, v0 quad_perm:[2,3,0,1] row_mask:0xf bank_mask:0xf
	s_waitcnt lgkmcnt(0)
	v_add_f32_e32 v0, v0, v10
	s_nop 1
	v_mov_b32_dpp v10, v0 quad_perm:[3,2,1,0] row_mask:0xf bank_mask:0xf
	s_nop 1
	v_mov_b32_dpp v10, v10 row_half_mirror row_mask:0xf bank_mask:0xf
	s_waitcnt lgkmcnt(0)
	v_add_f32_e32 v0, v0, v10
	s_nop 1
	v_mov_b32_dpp v10, v0 row_half_mirror row_mask:0xf bank_mask:0xf
	s_nop 1
	v_mov_b32_dpp v10, v10 row_mirror row_mask:0xf bank_mask:0xf
	s_waitcnt lgkmcnt(0)
	v_add_f32_e32 v0, v0, v10
	v_mov_b32_e32 v10, v0
	v_mov_b32_e32 v253, v0
	s_nop 1
	v_permlane16_swap_b32_e32 v10, v253
	s_mov_b32 s98, 0xffff
	s_mov_b32 s99, 0xffff
	v_cndmask_b32_e64 v10, v10, v253, s[98:99]
	s_and_saveexec_b64 s[12:13], s[34:35]
	s_cbranch_execz .LBB0_1014
	s_waitcnt lgkmcnt(0)
	v_add_f32_e32 v12, v0, v10
	v_lshlrev_b32_e32 v0, 5, v6
	v_lshl_add_u64 v[10:11], s[86:87], 0, v[0:1]
	global_store_dword v[10:11], v12, off

; template <int K> __device__ __forceinline__ float shx(float v) { static_assert(K < 32, "use sum32"); return __int_as_float(__builtin_amdgcn_ds_swizzle(__float_as_int(v), (K << 10) | 0x1f)); }
; #define SBAR() __builtin_amdgcn_sched_barrier(0)
; template <class TIn, class TOut, int ost, bool HAS_SS>
; __device__ __forceinline__ void causal_swa_block(const BlockRef<TIn, TOut>& cur_, const BlockRef<TIn, TOut>& nxt_, int skv, int W, char* lds, Seam<TIn>& S, int cbl  ) {
;     ...
;     for (int r = 0; r < 16; ++r) { const unsigned rowoff = ob0 + (unsigned)(((r & 3) + 8 * (r >> 2)) * ost * 2); float ss_ = 0.f;
; #pragma unroll
;         for (int d0 = 0; d0 < 4; ++d0) { const float v = o[d0][r] * rli[r]; ss_ += v * v;
;             const float vn = shx<1>(v);
;             if ((r32e & 1) == 0) *(unsigned*)(Ob + rowoff + d0 * 64) = cvtpk(v, vn); }
;         if (HAS_SS) { ss_ += shx<1>(ss_); ss_ += shx<2>(ss_); ss_ += shx<4>(ss_); ss_ += shx<8>(ss_); ss_ += shx<16>(ss_);
;             if (r32e == 0) *(float*)((char*)cur.SS + (unsigned)(wid * QBLK + 4 * hie + (r & 3) + 8 * (r >> 2)) * 32u) = ss_; }
;         SBAR(); }
.LBB0_1022:
	s_or_b64 exec, exec, s[12:13]
	v_mul_f32_e32 v6, v12, v12
	v_fmac_f32_e32 v6, v0, v0
	v_fmac_f32_e32 v6, v13, v13
	v_fmac_f32_e32 v6, v11, v11
	s_nop 1
	v_mov_b32_dpp v0, v6 quad_perm:[1,0,3,2] row_mask:0xf bank_mask:0xf
	s_waitcnt lgkmcnt(0)
	v_add_f32_e32 v0, v6, v0
	s_nop 1
	v_mov_b32_dpp v6, v0 quad_perm:[2,3,0,1] row_mask:0xf bank_mask:0xf
	s_waitcnt lgkmcnt(0)
	v_add_f32_e32 v0, v0, v6
	s_nop 1
	v_mov_b32_dpp v6, v0 quad_perm:[3,2,1,0] row_mask:0xf bank_mask:0xf
	s_nop 1
	v_mov_b32_dpp v6, v6 row_half_mirror row_mask:0xf bank_mask:0xf
	s_waitcnt lgkmcnt(0)
	v_add_f32_e32 v0, v0, v6
	s_nop 1
	v_mov_b32_dpp v6, v0 row_half_mirror row_mask:0xf bank_mask:0xf
	s_nop 1
	v_mov_b32_dpp v6, v6 row_mirror row_mask:0xf bank_mask:0xf
	s_waitcnt lgkmcnt(0)
	v_add_f32_e32 v0, v0, v6
	v_mov_b32_e32 v6, v0
	v_mov_b32_e32 v253, v0
	s_nop 1
	v_permlane16_swap_b32_e32 v6, v253
	s_mov_b32 s98, 0xffff
	s_mov_b32 s99, 0xffff
	v_cndmask_b32_e64 v6, v6, v253, s[98:99]
	s_and_saveexec_b64 s[12:13], s[34:35]
	s_cbranch_execz .LBB0_1024
	s_waitcnt lgkmcnt(0)
	v_add_f32_e32 v11, v0, v6
	v_lshlrev_b32_e32 v0, 5, v10
	v_lshl_add_u64 v[6:7], s[86:87], 0, v[0:1]
	global_store_dword v[6:7], v11, off

; template <int K> __device__ __forceinline__ float shx(float v) { static_assert(K < 32, "use sum32"); return __int_as_float(__builtin_amdgcn_ds_swizzle(__float_as_int(v), (K << 10) | 0x1f)); }
; #define SBAR() __builtin_amdgcn_sched_barrier(0)
; template <class TIn, class TOut, int ost, bool HAS_SS>
; __device__ __forceinline__ void causal_swa_block(const BlockRef<TIn, TOut>& cur_, const BlockRef<TIn, TOut>& nxt_, int skv, int W, char* lds, Seam<TIn>& S, int cbl  ) {
;     ...
;     for (int r = 0; r < 16; ++r) { const unsigned rowoff = ob0 + (unsigned)(((r & 3) + 8 * (r >> 2)) * ost * 2); float ss_ = 0.f;
; #pragma unroll
;         for (int d0 = 0; d0 < 4; ++d0) { const float v = o[d0][r] * rli[r]; ss_ += v * v;
;             const float vn = shx<1>(v);
;             if ((r32e & 1) == 0) *(unsigned*)(Ob + rowoff + d0 * 64) = cvtpk(v, vn); }
;         if (HAS_SS) { ss_ += shx<1>(ss_); ss_ += shx<2>(ss_); ss_ += shx<4>(ss_); ss_ += shx<8>(ss_); ss_ += shx<16>(ss_);
;             if (r32e == 0) *(float*)((char*)cur.SS + (unsigned)(wid * QBLK + 4 * hie + (r & 3) + 8 * (r >> 2)) * 32u) = ss_; }
;         SBAR(); }
.LBB0_1032:
	s_or_b64 exec, exec, s[12:13]
	v_mul_f32_e32 v6, v11, v11
	v_fmac_f32_e32 v6, v0, v0
	v_fmac_f32_e32 v6, v12, v12
	v_fmac_f32_e32 v6, v10, v10
	s_nop 1
	v_mov_b32_dpp v0, v6 quad_perm:[1,0,3,2] row_mask:0xf bank_mask:0xf
	s_waitcnt lgkmcnt(0)
	v_add_f32_e32 v0, v6, v0
	s_nop 1
	v_mov_b32_dpp v6, v0 quad_perm:[2,3,0,1] row_mask:0xf bank_mask:0xf
	s_waitcnt lgkmcnt(0)
	v_add_f32_e32 v0, v0, v6
	s_nop 1
	v_mov_b32_dpp v6, v0 quad_perm:[3,2,1,0] row_mask:0xf bank_mask:0xf
	s_nop 1
	v_mov_b32_dpp v6, v6 row_half_mirror row_mask:0xf bank_mask:0xf
	s_waitcnt lgkmcnt(0)
	v_add_f32_e32 v0, v0, v6
	s_nop 1
	v_mov_b32_dpp v6, v0 row_half_mirror row_mask:0xf bank_mask:0xf
	s_nop 1
	v_mov_b32_dpp v6, v6 row_mirror row_mask:0xf bank_mask:0xf
	s_waitcnt lgkmcnt(0)
	v_add_f32_e32 v0, v0, v6
	v_mov_b32_e32 v6, v0
	v_mov_b32_e32 v253, v0
	s_nop 1
	v_permlane16_swap_b32_e32 v6, v253
	s_mov_b32 s98, 0xffff
	s_mov_b32 s99, 0xffff
	v_cndmask_b32_e64 v6, v6, v253, s[98:99]
	s_and_saveexec_b64 s[12:13], s[34:35]
	s_cbranch_execz .LBB0_1034
	s_waitcnt lgkmcnt(0)
	v_add_f32_e32 v10, v0, v6
	v_lshlrev_b32_e32 v0, 5, v8
	v_lshl_add_u64 v[6:7], s[86:87], 0, v[0:1]
	global_store_dword v[6:7], v10, off

; template <int K> __device__ __forceinline__ float shx(float v) { static_assert(K < 32, "use sum32"); return __int_as_float(__builtin_amdgcn_ds_swizzle(__float_as_int(v), (K << 10) | 0x1f)); }
; #define SBAR() __builtin_amdgcn_sched_barrier(0)
; template <class TIn, class TOut, int ost, bool HAS_SS>
; __device__ __forceinline__ void causal_swa_block(const BlockRef<TIn, TOut>& cur_, const BlockRef<TIn, TOut>& nxt_, int skv, int W, char* lds, Seam<TIn>& S, int cbl  ) {
;     ...
;     for (int r = 0; r < 16; ++r) { const unsigned rowoff = ob0 + (unsigned)(((r & 3) + 8 * (r >> 2)) * ost * 2); float ss_ = 0.f;
; #pragma unroll
;         for (int d0 = 0; d0 < 4; ++d0) { const float v = o[d0][r] * rli[r]; ss_ += v * v;
;             const float vn = shx<1>(v);
;             if ((r32e & 1) == 0) *(unsigned*)(Ob + rowoff + d0 * 64) = cvtpk(v, vn); }
;         if (HAS_SS) { ss_ += shx<1>(ss_); ss_ += shx<2>(ss_); ss_ += shx<4>(ss_); ss_ += shx<8>(ss_); ss_ += shx<16>(ss_);
;             if (r32e == 0) *(float*)((char*)cur.SS + (unsigned)(wid * QBLK + 4 * hie + (r & 3) + 8 * (r >> 2)) * 32u) = ss_; }
;         SBAR(); }
.LBB0_1042:
	s_or_b64 exec, exec, s[12:13]
	v_mul_f32_e32 v6, v10, v10
	v_fmac_f32_e32 v6, v0, v0
	v_fmac_f32_e32 v6, v11, v11
	v_fmac_f32_e32 v6, v9, v9
	s_nop 1
	v_mov_b32_dpp v0, v6 quad_perm:[1,0,3,2] row_mask:0xf bank_mask:0xf
	s_waitcnt lgkmcnt(0)
	v_add_f32_e32 v0, v6, v0
	s_nop 1
	v_mov_b32_dpp v6, v0 quad_perm:[2,3,0,1] row_mask:0xf bank_mask:0xf
	s_waitcnt lgkmcnt(0)
	v_add_f32_e32 v0, v0, v6
	s_nop 1
	v_mov_b32_dpp v6, v0 quad_perm:[3,2,1,0] row_mask:0xf bank_mask:0xf
	s_nop 1
	v_mov_b32_dpp v6, v6 row_half_mirror row_mask:0xf bank_mask:0xf
	s_waitcnt lgkmcnt(0)
	v_add_f32_e32 v0, v0, v6
	s_nop 1
	v_mov_b32_dpp v6, v0 row_half_mirror row_mask:0xf bank_mask:0xf
	s_nop 1
	v_mov_b32_dpp v6, v6 row_mirror row_mask:0xf bank_mask:0xf
	s_waitcnt lgkmcnt(0)
	v_add_f32_e32 v0, v0, v6
	v_mov_b32_e32 v6, v0
	v_mov_b32_e32 v253, v0
	s_nop 1
	v_permlane16_swap_b32_e32 v6, v253
	s_mov_b32 s98, 0xffff
	s_mov_b32 s99, 0xffff
	v_cndmask_b32_e64 v6, v6, v253, s[98:99]
	s_and_saveexec_b64 s[12:13], s[34:35]
	s_cbranch_execz .LBB0_1044
	s_waitcnt lgkmcnt(0)
	v_add_f32_e32 v9, v0, v6
	v_lshlrev_b32_e32 v0, 5, v8
	v_lshl_add_u64 v[6:7], s[86:87], 0, v[0:1]
	global_store_dword v[6:7], v9, off

; template <int K> __device__ __forceinline__ float shx(float v) { static_assert(K < 32, "use sum32"); return __int_as_float(__builtin_amdgcn_ds_swizzle(__float_as_int(v), (K << 10) | 0x1f)); }
; #define SBAR() __builtin_amdgcn_sched_barrier(0)
; template <class TIn, class TOut, int ost, bool HAS_SS>
; __device__ __forceinline__ void causal_swa_block(const BlockRef<TIn, TOut>& cur_, const BlockRef<TIn, TOut>& nxt_, int skv, int W, char* lds, Seam<TIn>& S, int cbl  ) {
;     ...
;     for (int r = 0; r < 16; ++r) { const unsigned rowoff = ob0 + (unsigned)(((r & 3) + 8 * (r >> 2)) * ost * 2); float ss_ = 0.f;
; #pragma unroll
;         for (int d0 = 0; d0 < 4; ++d0) { const float v = o[d0][r] * rli[r]; ss_ += v * v;
;             const float vn = shx<1>(v);
;             if ((r32e & 1) == 0) *(unsigned*)(Ob + rowoff + d0 * 64) = cvtpk(v, vn); }
;         if (HAS_SS) { ss_ += shx<1>(ss_); ss_ += shx<2>(ss_); ss_ += shx<4>(ss_); ss_ += shx<8>(ss_); ss_ += shx<16>(ss_);
;             if (r32e == 0) *(float*)((char*)cur.SS + (unsigned)(wid * QBLK + 4 * hie + (r & 3) + 8 * (r >> 2)) * 32u) = ss_; }
;         SBAR(); }
.LBB0_1052:
	s_or_b64 exec, exec, s[12:13]
	v_mul_f32_e32 v6, v9, v9
	v_fmac_f32_e32 v6, v0, v0
	v_fmac_f32_e32 v6, v10, v10
	v_fmac_f32_e32 v6, v8, v8
	s_nop 1
	v_mov_b32_dpp v0, v6 quad_perm:[1,0,3,2] row_mask:0xf bank_mask:0xf
	s_waitcnt lgkmcnt(0)
	v_add_f32_e32 v0, v6, v0
	s_nop 1
	v_mov_b32_dpp v6, v0 quad_perm:[2,3,0,1] row_mask:0xf bank_mask:0xf
	s_waitcnt lgkmcnt(0)
	v_add_f32_e32 v0, v0, v6
	s_nop 1
	v_mov_b32_dpp v6, v0 quad_perm:[3,2,1,0] row_mask:0xf bank_mask:0xf
	s_nop 1
	v_mov_b32_dpp v6, v6 row_half_mirror row_mask:0xf bank_mask:0xf
	s_waitcnt lgkmcnt(0)
	v_add_f32_e32 v0, v0, v6
	s_nop 1
	v_mov_b32_dpp v6, v0 row_half_mirror row_mask:0xf bank_mask:0xf
	s_nop 1
	v_mov_b32_dpp v6, v6 row_mirror row_mask:0xf bank_mask:0xf
	s_waitcnt lgkmcnt(0)
	v_add_f32_e32 v0, v0, v6
	v_mov_b32_e32 v6, v0
	v_mov_b32_e32 v253, v0
	s_nop 1
	v_permlane16_swap_b32_e32 v6, v253
	s_mov_b32 s98, 0xffff
	s_mov_b32 s99, 0xffff
	v_cndmask_b32_e64 v6, v6, v253, s[98:99]
	s_and_saveexec_b64 s[12:13], s[34:35]
	s_cbranch_execz .LBB0_1054
	s_waitcnt lgkmcnt(0)
	v_add_f32_e32 v8, v0, v6
	v_lshlrev_b32_e32 v0, 5, v2
	v_lshl_add_u64 v[6:7], s[86:87], 0, v[0:1]
	global_store_dword v[6:7], v8, off

; template <int K> __device__ __forceinline__ float shx(float v) { static_assert(K < 32, "use sum32"); return __int_as_float(__builtin_amdgcn_ds_swizzle(__float_as_int(v), (K << 10) | 0x1f)); }
; #define SBAR() __builtin_amdgcn_sched_barrier(0)
; template <class TIn, class TOut, int ost, bool HAS_SS>
; __device__ __forceinline__ void causal_swa_block(const BlockRef<TIn, TOut>& cur_, const BlockRef<TIn, TOut>& nxt_, int skv, int W, char* lds, Seam<TIn>& S, int cbl  ) {
;     ...
;     for (int r = 0; r < 16; ++r) { const unsigned rowoff = ob0 + (unsigned)(((r & 3) + 8 * (r >> 2)) * ost * 2); float ss_ = 0.f;
; #pragma unroll
;         for (int d0 = 0; d0 < 4; ++d0) { const float v = o[d0][r] * rli[r]; ss_ += v * v;
;             const float vn = shx<1>(v);
;             if ((r32e & 1) == 0) *(unsigned*)(Ob + rowoff + d0 * 64) = cvtpk(v, vn); }
;         if (HAS_SS) { ss_ += shx<1>(ss_); ss_ += shx<2>(ss_); ss_ += shx<4>(ss_); ss_ += shx<8>(ss_); ss_ += shx<16>(ss_);
;             if (r32e == 0) *(float*)((char*)cur.SS + (unsigned)(wid * QBLK + 4 * hie + (r & 3) + 8 * (r >> 2)) * 32u) = ss_; }
;         SBAR(); }
.LBB0_1062:
	s_or_b64 exec, exec, s[12:13]
	v_mul_f32_e32 v2, v8, v8
	v_fmac_f32_e32 v2, v0, v0
	v_fmac_f32_e32 v2, v9, v9
	v_fmac_f32_e32 v2, v7, v7
	s_nop 1
	v_mov_b32_dpp v0, v2 quad_perm:[1,0,3,2] row_mask:0xf bank_mask:0xf
	s_waitcnt lgkmcnt(0)
	v_add_f32_e32 v0, v2, v0
	s_nop 1
	v_mov_b32_dpp v2, v0 quad_perm:[2,3,0,1] row_mask:0xf bank_mask:0xf
	s_waitcnt lgkmcnt(0)
	v_add_f32_e32 v0, v0, v2
	s_nop 1
	v_mov_b32_dpp v2, v0 quad_perm:[3,2,1,0] row_mask:0xf bank_mask:0xf
	s_nop 1
	v_mov_b32_dpp v2, v2 row_half_mirror row_mask:0xf bank_mask:0xf
	s_waitcnt lgkmcnt(0)
	v_add_f32_e32 v0, v0, v2
	s_nop 1
	v_mov_b32_dpp v2, v0 row_half_mirror row_mask:0xf bank_mask:0xf
	s_nop 1
	v_mov_b32_dpp v2, v2 row_mirror row_mask:0xf bank_mask:0xf
	s_waitcnt lgkmcnt(0)
	v_add_f32_e32 v0, v0, v2
	v_mov_b32_e32 v2, v0
	v_mov_b32_e32 v253, v0
	s_nop 1
	v_permlane16_swap_b32_e32 v2, v253
	s_mov_b32 s98, 0xffff
	s_mov_b32 s99, 0xffff
	v_cndmask_b32_e64 v2, v2, v253, s[98:99]
	s_and_saveexec_b64 s[12:13], s[34:35]
	s_cbranch_execz .LBB0_1064
	s_waitcnt lgkmcnt(0)
	v_add_f32_e32 v7, v0, v2
	v_lshlrev_b32_e32 v0, 5, v6
	v_lshl_add_u64 v[2:3], s[86:87], 0, v[0:1]
	global_store_dword v[2:3], v7, off

; template <int K> __device__ __forceinline__ float shx(float v) { static_assert(K < 32, "use sum32"); return __int_as_float(__builtin_amdgcn_ds_swizzle(__float_as_int(v), (K << 10) | 0x1f)); }
; #define SBAR() __builtin_amdgcn_sched_barrier(0)
; template <class TIn, class TOut, int ost, bool HAS_SS>
; __device__ __forceinline__ void causal_swa_block(const BlockRef<TIn, TOut>& cur_, const BlockRef<TIn, TOut>& nxt_, int skv, int W, char* lds, Seam<TIn>& S, int cbl  ) {
;     ...
;     for (int r = 0; r < 16; ++r) { const unsigned rowoff = ob0 + (unsigned)(((r & 3) + 8 * (r >> 2)) * ost * 2); float ss_ = 0.f;
; #pragma unroll
;         for (int d0 = 0; d0 < 4; ++d0) { const float v = o[d0][r] * rli[r]; ss_ += v * v;
;             const float vn = shx<1>(v);
;             if ((r32e & 1) == 0) *(unsigned*)(Ob + rowoff + d0 * 64) = cvtpk(v, vn); }
;         if (HAS_SS) { ss_ += shx<1>(ss_); ss_ += shx<2>(ss_); ss_ += shx<4>(ss_); ss_ += shx<8>(ss_); ss_ += shx<16>(ss_);
;             if (r32e == 0) *(float*)((char*)cur.SS + (unsigned)(wid * QBLK + 4 * hie + (r & 3) + 8 * (r >> 2)) * 32u) = ss_; }
;         SBAR(); }
.LBB0_1072:
	s_or_b64 exec, exec, s[12:13]
	v_mul_f32_e32 v2, v7, v7
	v_fmac_f32_e32 v2, v0, v0
	v_fmac_f32_e32 v2, v8, v8
	v_fmac_f32_e32 v2, v6, v6
	s_nop 1
	v_mov_b32_dpp v0, v2 quad_perm:[1,0,3,2] row_mask:0xf bank_mask:0xf
	s_waitcnt lgkmcnt(0)
	v_add_f32_e32 v0, v2, v0
	s_nop 1
	v_mov_b32_dpp v2, v0 quad_perm:[2,3,0,1] row_mask:0xf bank_mask:0xf
	s_waitcnt lgkmcnt(0)
	v_add_f32_e32 v0, v0, v2
	s_nop 1
	v_mov_b32_dpp v2, v0 quad_perm:[3,2,1,0] row_mask:0xf bank_mask:0xf
	s_nop 1
	v_mov_b32_dpp v2, v2 row_half_mirror row_mask:0xf bank_mask:0xf
	s_waitcnt lgkmcnt(0)
	v_add_f32_e32 v0, v0, v2
	s_nop 1
	v_mov_b32_dpp v2, v0 row_half_mirror row_mask:0xf bank_mask:0xf
	s_nop 1
	v_mov_b32_dpp v2, v2 row_mirror row_mask:0xf bank_mask:0xf
	s_waitcnt lgkmcnt(0)
	v_add_f32_e32 v0, v0, v2
	v_mov_b32_e32 v2, v0
	v_mov_b32_e32 v253, v0
	s_nop 1
	v_permlane16_swap_b32_e32 v2, v253
	s_mov_b32 s98, 0xffff
	s_mov_b32 s99, 0xffff
	v_cndmask_b32_e64 v2, v2, v253, s[98:99]
	s_and_saveexec_b64 s[12:13], s[34:35]
	s_cbranch_execz .LBB0_1074
	s_waitcnt lgkmcnt(0)
	v_add_f32_e32 v6, v0, v2
	v_lshlrev_b32_e32 v0, 5, v4
	v_lshl_add_u64 v[2:3], s[86:87], 0, v[0:1]
	global_store_dword v[2:3], v6, off

; template <int K> __device__ __forceinline__ float shx(float v) { static_assert(K < 32, "use sum32"); return __int_as_float(__builtin_amdgcn_ds_swizzle(__float_as_int(v), (K << 10) | 0x1f)); }
; #define SBAR() __builtin_amdgcn_sched_barrier(0)
; template <class TIn, class TOut, int ost, bool HAS_SS>
; __device__ __forceinline__ void causal_swa_block(const BlockRef<TIn, TOut>& cur_, const BlockRef<TIn, TOut>& nxt_, int skv, int W, char* lds, Seam<TIn>& S, int cbl  ) {
;     ...
;     for (int r = 0; r < 16; ++r) { const unsigned rowoff = ob0 + (unsigned)(((r & 3) + 8 * (r >> 2)) * ost * 2); float ss_ = 0.f;
; #pragma unroll
;         for (int d0 = 0; d0 < 4; ++d0) { const float v = o[d0][r] * rli[r]; ss_ += v * v;
;             const float vn = shx<1>(v);
;             if ((r32e & 1) == 0) *(unsigned*)(Ob + rowoff + d0 * 64) = cvtpk(v, vn); }
;         if (HAS_SS) { ss_ += shx<1>(ss_); ss_ += shx<2>(ss_); ss_ += shx<4>(ss_); ss_ += shx<8>(ss_); ss_ += shx<16>(ss_);
;             if (r32e == 0) *(float*)((char*)cur.SS + (unsigned)(wid * QBLK + 4 * hie + (r & 3) + 8 * (r >> 2)) * 32u) = ss_; }
;         SBAR(); }
.LBB0_1082:
	s_or_b64 exec, exec, s[12:13]
	v_mul_f32_e32 v0, v0, v0
	v_fmac_f32_e32 v0, v5, v5
	v_fmac_f32_e32 v0, v7, v7
	v_fmac_f32_e32 v0, v6, v6
	s_nop 1
	v_mov_b32_dpp v2, v0 quad_perm:[1,0,3,2] row_mask:0xf bank_mask:0xf
	s_waitcnt lgkmcnt(0)
	v_add_f32_e32 v0, v0, v2
	s_nop 1
	v_mov_b32_dpp v2, v0 quad_perm:[2,3,0,1] row_mask:0xf bank_mask:0xf
	s_waitcnt lgkmcnt(0)
	v_add_f32_e32 v0, v0, v2
	s_nop 1
	v_mov_b32_dpp v2, v0 quad_perm:[3,2,1,0] row_mask:0xf bank_mask:0xf
	s_nop 1
	v_mov_b32_dpp v2, v2 row_half_mirror row_mask:0xf bank_mask:0xf
	s_waitcnt lgkmcnt(0)
	v_add_f32_e32 v0, v0, v2
	s_nop 1
	v_mov_b32_dpp v2, v0 row_half_mirror row_mask:0xf bank_mask:0xf
	s_nop 1
	v_mov_b32_dpp v2, v2 row_mirror row_mask:0xf bank_mask:0xf
	s_waitcnt lgkmcnt(0)
	v_add_f32_e32 v0, v0, v2
	v_mov_b32_e32 v2, v0
	v_mov_b32_e32 v253, v0
	s_nop 1
	v_permlane16_swap_b32_e32 v2, v253
	s_mov_b32 s98, 0xffff
	s_mov_b32 s99, 0xffff
	v_cndmask_b32_e64 v2, v2, v253, s[98:99]
	s_and_saveexec_b64 s[12:13], s[34:35]
	s_cbranch_execz .LBB0_882
	s_waitcnt lgkmcnt(0)
	v_add_f32_e32 v5, v0, v2
	v_lshlrev_b32_e32 v0, 5, v4
	v_lshl_add_u64 v[2:3], s[86:87], 0, v[0:1]
	global_store_dword v[2:3], v5, off
	s_branch .LBB0_882

; __global__ void __launch_bounds__(NTHR, LB2) hymba_fwd(Args a) {
	.amdhsa_kernel _Z9hymba_fwd4Args
		.amdhsa_group_segment_fixed_size 0
		.amdhsa_private_segment_fixed_size 0
		.amdhsa_kernarg_size 488
		.amdhsa_user_sgpr_count 2
		.amdhsa_user_sgpr_dispatch_ptr 0
		.amdhsa_user_sgpr_queue_ptr 0
		.amdhsa_user_sgpr_kernarg_segment_ptr 1
		.amdhsa_user_sgpr_dispatch_id 0
		.amdhsa_user_sgpr_kernarg_preload_length 0
		.amdhsa_user_sgpr_kernarg_preload_offset 0
		.amdhsa_user_sgpr_private_segment_size 0
		.amdhsa_uses_dynamic_stack 0
		.amdhsa_enable_private_segment 0
		.amdhsa_system_sgpr_workgroup_id_x 1
		.amdhsa_system_sgpr_workgroup_id_y 0
		.amdhsa_system_sgpr_workgroup_id_z 0
		.amdhsa_system_sgpr_workgroup_info 0
		.amdhsa_system_vgpr_workitem_id 2
		.amdhsa_next_free_vgpr 256
		.amdhsa_next_free_sgpr 102
		.amdhsa_accum_offset 256
		.amdhsa_reserve_vcc 1
		.amdhsa_float_round_mode_32 0
		.amdhsa_float_round_mode_16_64 0
		.amdhsa_float_denorm_mode_32 3
		.amdhsa_float_denorm_mode_16_64 3
		.amdhsa_dx10_clamp 1
		.amdhsa_ieee_mode 1
		.amdhsa_fp16_overflow 0
		.amdhsa_tg_split 0
		.amdhsa_exception_fp_ieee_invalid_op 0
		.amdhsa_exception_fp_denorm_src 0
		.amdhsa_exception_fp_ieee_div_zero 0
		.amdhsa_exception_fp_ieee_overflow 0
		.amdhsa_exception_fp_ieee_underflow 0
		.amdhsa_exception_fp_ieee_inexact 0
		.amdhsa_exception_int_div_zero 0
	.end_amdhsa_kernel

; __global__ void __launch_bounds__(NTHR, LB2) hymba_fwd(Args a) {
amdhsa.kernels:
  - .agpr_count:     0
    .args:
      - .offset:         0
        .size:           232
        .value_kind:     by_value
      - .offset:         232
        .size:           4
        .value_kind:     hidden_block_count_x
      - .offset:         236
        .size:           4
        .value_kind:     hidden_block_count_y
      - .offset:         240
        .size:           4
        .value_kind:     hidden_block_count_z
      - .offset:         244
        .size:           2
        .value_kind:     hidden_group_size_x
      - .offset:         246
        .size:           2
        .value_kind:     hidden_group_size_y
      - .offset:         248
        .size:           2
        .value_kind:     hidden_group_size_z
      - .offset:         250
        .size:           2
        .value_kind:     hidden_remainder_x
      - .offset:         252
        .size:           2
        .value_kind:     hidden_remainder_y
      - .offset:         254
        .size:           2
        .value_kind:     hidden_remainder_z
      - .offset:         272
        .size:           8
        .value_kind:     hidden_global_offset_x
      - .offset:         280
        .size:           8
        .value_kind:     hidden_global_offset_y
      - .offset:         288
        .size:           8
        .value_kind:     hidden_global_offset_z
      - .offset:         296
        .size:           2
        .value_kind:     hidden_grid_dims
      - .offset:         320
        .size:           8
        .value_kind:     hidden_multigrid_sync_arg
      - .offset:         352
        .size:           4
        .value_kind:     hidden_dynamic_lds_size
    .group_segment_fixed_size: 0
    .kernarg_segment_align: 8
    .kernarg_segment_size: 488
    .language:       OpenCL C
    .language_version:
      - 2
      - 0
    .max_flat_workgroup_size: 512
    .name:           _Z9hymba_fwd4Args
    .private_segment_fixed_size: 0
    .sgpr_count:     108
    .sgpr_spill_count: 139
    .symbol:         _Z9hymba_fwd4Args.kd
    .uniform_work_group_size: 1
    .uses_dynamic_stack: false
    .vgpr_count:     256
    .vgpr_spill_count: 0
    .wavefront_size: 64
